# LN2(l)->in-proj(l+1) grid barrier replaced by completion records (8 LN2 tiles per row block + 64 weight-conversion workgroups); in-proj polls (async for later tiles) and reads operands with sc1 DMA lo
# speedup vs baseline: 1.0336x; 1.0062x over previous
.LBB0_8:
	s_cmp_le_i32 s18, s80
	s_cbranch_scc1 .LBB0_74
	s_cmp_eq_u32 s18, 5
	s_cbranch_scc1 .LBB0_74
	s_cmp_eq_u32 s18, 7
	s_cbranch_scc1 .LBB0_74
	s_cmp_eq_u32 s18, 12
	s_cbranch_scc1 .LBB0_74
	s_cmp_eq_u32 s18, 17
	s_cbranch_scc1 .LBB0_74
	s_cmp_eq_u32 s18, 6
	s_cbranch_scc1 .LBB0_74
	s_cmp_eq_u32 s18, 11
	s_cbranch_scc1 .LBB0_74
	s_cmp_eq_u32 s18, 16
	s_cbranch_scc1 .LBB0_74
	s_cmp_eq_u32 s18, 21
	s_cbranch_scc1 .LBB0_74
	s_cmp_eq_u32 s18, 10
	s_cbranch_scc1 .LBB0_74
	s_cmp_eq_u32 s18, 15
	s_cbranch_scc1 .LBB0_74
	s_cmp_eq_u32 s18, 20
	s_cbranch_scc1 .LBB0_74
	v_readlane_b32 s0, v253, 19
	v_readlane_b32 s1, v253, 20
	s_andn2_b64 vcc, exec, s[0:1]
	s_cbranch_vccnz .LBB0_21
	s_barrier
	s_mov_b64 s[0:1], exec
	v_readlane_b32 s8, v253, 21
	v_readlane_b32 s9, v253, 22
	s_and_b64 s[8:9], s[0:1], s[8:9]
	s_mov_b64 exec, s[8:9]
	s_cbranch_execz .LBB0_20
	buffer_wbl2 sc1
	s_waitcnt vmcnt(0)
	s_load_dwordx2 s[22:23], s[78:79], 0x58
	s_mov_b64 s[26:27], exec
	v_mbcnt_lo_u32_b32 v2, s26, 0
	v_mbcnt_hi_u32_b32 v2, s27, v2
	v_cmp_eq_u32_e32 vcc, 0, v2
	s_waitcnt lgkmcnt(0)
	global_load_dword v0, v1, s[22:23] offset:40
	s_and_saveexec_b64 s[34:35], vcc
	s_cbranch_execz .LBB0_13
	s_bcnt1_i32_b64 s5, s[26:27]
	v_mov_b32_e32 v3, s5
	global_atomic_add v3, v1, v3, s[22:23] offset:32 sc0

.Lcv1_done:
	s_waitcnt vmcnt(0)
	s_barrier
	v_readfirstlane_b32 s8, v137
	s_cmp_lt_u32 s8, 64
	s_cbranch_scc0 .LBB0_126
	v_readlane_b32 s8, v253, 0
	s_add_i32 s8, s8, 0xffffff40
	s_lshl_b32 s8, s8, 4
	v_readlane_b32 s9, v255, 40
	s_add_i32 s9, s9, 0x5d0e4000
	v_mov_b32_e32 v2, s8
	v_mov_b32_e32 v4, s9
	v_mov_b32_e32 v5, s9
	v_mov_b32_e32 v6, s9
	v_mov_b32_e32 v7, s9
	s_add_u32 s0, s94, 0xcbcd000
	s_addc_u32 s1, s95, 0
	s_mov_b64 exec, 1
	global_store_dwordx4 v2, v[4:7], s[0:1] sc1
	s_mov_b64 exec, -1

.LBB0_339:
	s_and_b64 vcc, exec, s[0:1]
	s_cbranch_vccz .LBB0_394
	v_readlane_b32 s0, v255, 44
	s_cmp_gt_i32 s0, -2
	s_mov_b64 s[0:1], -1
	s_cbranch_scc0 .LBB0_406
	v_readlane_b32 s0, v255, 44
	s_cmp_gt_i32 s0, -1
	s_mov_b64 s[0:1], -1
	s_cbranch_scc0 .LBB0_396
	s_mov_b64 s[22:23], 0
	s_mov_b64 s[26:27], 0
	v_mov_b32_e32 v0, v137
	s_nop 0
	v_readfirstlane_b32 s0, v0
	s_ashr_i32 s72, s0, 6
	v_readlane_b32 s0, v254, 43
	v_readlane_b32 s1, v254, 44
	s_andn2_b64 vcc, exec, s[0:1]
	s_cbranch_vccnz .LBB0_395
	v_bfe_u32 v4, v0, 3, 3
	v_lshl_or_b32 v2, s72, 5, v4
	s_add_u32 s0, s94, s22
	v_ashrrev_i32_e32 v3, 31, v2
	s_addc_u32 s1, s95, s23
	v_lshlrev_b64 v[2:3], 11, v[2:3]
	v_bitop3_b32 v5, v4, v0, 7 bitop3:0x78
	s_lshl_b64 s[8:9], s[26:27], 2
	v_lshlrev_b32_e32 v102, 4, v5
	v_mov_b32_e32 v103, v1
	v_lshl_add_u64 v[104:105], s[0:1], 0, v[2:3]
	s_add_u32 s8, s92, s8
	v_readlane_b32 s12, v255, 40
	v_lshl_add_u64 v[2:3], v[104:105], 0, v[102:103]
	s_mov_b64 s[16:17], 0x7b48000
	s_addc_u32 s9, s93, s9
	s_mul_i32 s14, s12, 0x6c0000
	s_and_b32 s19, s72, 1
	s_ashr_i32 s20, s72, 1
	v_lshl_add_u64 v[106:107], v[2:3], 0, s[16:17]
	v_lshl_or_b32 v2, s72, 4, v4
	v_readlane_b32 s13, v255, 41
	s_mov_b32 s26, s12
	s_mul_hi_u32 s6, s12, 0x6c0000
	s_add_u32 s12, s0, s14
	v_ashrrev_i32_e32 v3, 31, v2
	s_addc_u32 s13, s1, s6
	v_lshlrev_b64 v[2:3], 11, v[2:3]
	v_lshl_add_u64 v[4:5], s[12:13], 0, v[2:3]
	s_lshl_b32 s11, s72, 12
	s_lshl_b32 s12, s72, 11
	s_lshl_b32 s13, s20, 13
	s_lshl_b32 s70, s20, 6
	s_lshl_b32 s20, s19, 13
	s_lshl_b32 s71, s19, 6
	s_add_u32 s73, s0, 0x8748000
	s_addc_u32 s74, s1, 0
	s_add_u32 s42, s0, 0x11e58000
	v_bfe_u32 v101, v0, 4, 2
	s_addc_u32 s43, s1, 0
	v_and_b32_e32 v100, 15, v0
	v_lshl_add_u64 v[108:109], v[4:5], 0, v[102:103]
	v_bitop3_b32 v4, v101, v0, 7 bitop3:0x78
	s_add_u32 s44, s0, 0x11e59000
	v_lshlrev_b32_e32 v124, 4, v4
	v_or_b32_e32 v4, s70, v100
	s_addc_u32 s45, s1, 0
	v_and_b32_e32 v6, 7, v0
	v_lshlrev_b32_e32 v125, 7, v4
	v_or_b32_e32 v4, s71, v100
	s_add_u32 s14, s22, s14
	v_lshlrev_b32_e32 v127, 7, v4
	v_bitop3_b32 v4, v101, v6, 4 bitop3:0x36
	s_mulk_i32 s72, 0x4100
	v_lshlrev_b32_e32 v6, 2, v100
	v_mov_b32_e32 v7, v1
	s_addc_u32 s6, s23, s6
	v_lshlrev_b32_e32 v122, 7, v100
	v_lshlrev_b32_e32 v128, 4, v4
	v_and_b32_e32 v4, 16, v0
	v_lshl_add_u64 v[8:9], s[0:1], 0, v[6:7]
	v_mul_u32_u24_e32 v7, 0x104, v101
	v_or_b32_e32 v6, s72, v6
	s_movk_i32 s16, 0x104
	v_readlane_b32 s48, v254, 53
	s_add_u32 s22, s94, s14
	v_and_b32_e32 v98, 63, v0
	v_or_b32_e32 v123, s13, v122
	v_or_b32_e32 v126, s20, v122
	s_waitcnt vmcnt(0)
	v_bitop3_b32 v15, v0, 16, 63 bitop3:0x6c
	v_cmp_eq_u32_e64 s[40:41], 0, v4
	v_and_b32_e32 v4, 31, v0
	v_lshl_or_b32 v0, s26, 4, v100
	s_mov_b64 s[26:27], 0xbd78000
	v_mad_u32_u24 v129, v101, s16, v6
	v_lshl_add_u32 v177, v7, 2, v6
	v_mov_b32_e32 v6, s72
	v_readlane_b32 s56, v254, 61
	v_readlane_b32 s57, v254, 62
	s_addc_u32 s23, s95, s6
	v_or_b32_e32 v5, 0x800, v125
	v_or_b32_e32 v10, 0x1000, v125
	v_or_b32_e32 v11, 0x1800, v125
	v_or_b32_e32 v12, 0x800, v127
	v_or_b32_e32 v13, 0x1000, v127
	v_or_b32_e32 v14, 0x1800, v127
	v_lshl_add_u64 v[110:111], v[8:9], 0, s[26:27]
	v_mad_u32_u24 v179, v98, s16, v6
	v_readlane_b32 s54, v254, 59
	v_readlane_b32 s55, v254, 60
	v_lshl_add_u64 v[112:113], v[0:1], 2, s[56:57]
	v_or_b32_e32 v0, 0x18000, v128
	v_or_b32_e32 v6, 0x20000, v126
	v_or_b32_e32 v7, 0x20000, v128
	v_add_u32_e32 v8, 0xc000, v123
	v_add_u32_e32 v9, 0xc000, v125
	v_or_b32_e32 v16, 0xc000, v126
	v_or_b32_e32 v17, 0xc000, v127
	v_lshl_add_u64 v[114:115], s[22:23], 0, v[2:3]
	v_or_b32_e32 v181, s13, v128
	v_or_b32_e32 v2, s20, v124
	s_add_i32 s13, s13, 0xc000
	v_add_u32_e32 v210, v124, v126
	v_cmp_gt_u32_e64 s[38:39], 32, v98
	v_add_u32_e32 v130, 0x1450, v129
	v_or_b32_e32 v131, 24, v101
	v_add_u32_e32 v132, 0x1860, v129
	v_or_b32_e32 v133, 28, v101
	v_add_u32_e32 v134, 0x1c70, v129
	v_or_b32_e32 v135, 32, v101
	v_add_u32_e32 v161, 0x2080, v129
	v_or_b32_e32 v163, 36, v101
	v_add_u32_e32 v164, 0x2490, v129
	v_or_b32_e32 v165, 40, v101
	v_add_u32_e32 v166, 0x28a0, v129
	v_or_b32_e32 v167, 44, v101
	v_add_u32_e32 v168, 0x2cb0, v129
	v_or_b32_e32 v169, 48, v101
	v_add_u32_e32 v170, 0x30c0, v129
	v_or_b32_e32 v171, 52, v101
	v_add_u32_e32 v172, 0x34d0, v129
	v_or_b32_e32 v173, 56, v101
	v_add_u32_e32 v174, 0x38e0, v129
	v_or_b32_e32 v175, 60, v101
	v_add_u32_e32 v176, 0x3cf0, v129
	v_lshl_or_b32 v178, v98, 2, s72
	s_mov_b64 s[54:55], 0x7b50180
	v_add_u32_e32 v180, 0x18000, v123
	v_mov_b32_e32 v99, v100
	v_or_b32_e32 v182, 0x15000, v2
	v_or_b32_e32 v201, 0x14800, v2
	v_or_b32_e32 v202, 0x14000, v2
	v_or_b32_e32 v203, s20, v128
	v_or_b32_e32 v204, s13, v124
	v_add_u32_e32 v205, v8, v128
	v_add_u32_e32 v206, v9, v128
	v_add_u32_e32 v207, v16, v128
	v_add_u32_e32 v208, v17, v128
	v_add3_u32 v209, v125, v124, s29
	v_or_b32_e32 v211, 0x20000, v210
	v_add_u32_e32 v212, v124, v127
	v_add_u32_e32 v213, v0, v5
	v_add_u32_e32 v214, v0, v10
	v_add_u32_e32 v215, v0, v11
	v_add_u32_e32 v216, v6, v128
	v_add_u32_e32 v217, v7, v12
	v_add_u32_e32 v218, v7, v13
	v_add_u32_e32 v219, v7, v14
	v_lshlrev_b32_e32 v0, 1, v98
	v_lshlrev_b32_e32 v220, 2, v15
	v_lshlrev_b32_e32 v116, 1, v4
	v_readlane_b32 s75, v253, 0
	v_readlane_b32 s49, v254, 54
	v_readlane_b32 s50, v254, 55
	v_readlane_b32 s51, v254, 56
	v_readlane_b32 s52, v254, 57
	v_readlane_b32 s53, v254, 58
	v_readlane_b32 s58, v254, 63
	v_readlane_b32 s59, v255, 0
	v_readlane_b32 s60, v255, 1
	v_readlane_b32 s61, v255, 2
	v_readlane_b32 s62, v255, 3
	v_readlane_b32 s63, v255, 4
	s_mov_b32 s66, 0
	s_mov_b32 s67, 0
	s_branch .LBB0_346

.LBB0_346:
	s_mul_hi_i32 s6, s75, 0x2aaaaaab
	s_lshr_b32 s13, s6, 31
	s_ashr_i32 s6, s6, 2
	s_add_i32 s6, s6, s13
	s_mul_i32 s13, s6, 24
	s_sub_i32 s13, s75, s13
	v_readlane_b32 s64, v255, 40
	s_cmp_eq_u32 s64, 0
	s_cbranch_scc1 .Lip_nodep
	s_add_i32 s64, s64, 0x5d0e2fff
	s_cmp_eq_u32 s67, 0
	s_cbranch_scc1 .Lip_block
	v_cmp_ne_u32_e32 vcc, s64, v242
	s_cbranch_vccz .Lip_ok
.Lip_block:
	s_lshl_b32 s65, s13, 7
	s_add_u32 s46, s94, 0xcbcc000
	s_addc_u32 s47, s95, 0
	v_and_b32_e32 v66, 7, v137
	v_lshlrev_b32_e32 v66, 4, v66
	v_add_u32_e32 v66, s65, v66
	s_mov_b32 s65, 0x100000
.Lip_poll:
	global_load_dwordx4 v[68:71], v66, s[46:47] sc1
	s_waitcnt vmcnt(0)
	v_cmp_ne_u32_e32 vcc, s64, v68
	s_cbranch_vccz .Lip_ok
	s_sleep 1
	s_add_i32 s65, s65, -1
	s_cmp_lg_u32 s65, 0
	s_cbranch_scc1 .Lip_poll
.Lip_ok:
	s_cmp_lg_u32 s66, 0
	s_cbranch_scc1 .Lip_nodep
	s_add_i32 s64, s64, 0x1000
	s_add_u32 s46, s94, 0xcbcd000
	s_addc_u32 s47, s95, 0
	v_and_b32_e32 v66, 63, v137
	v_lshlrev_b32_e32 v66, 4, v66
	s_mov_b32 s65, 0x100000

.Lip_cok:
	s_mov_b32 s66, 1
.Lip_nodep:
	s_lshl_b32 s26, s13, 8
	s_ashr_i32 s27, s26, 31
	s_lshl_b64 s[34:35], s[26:27], 11
	s_mov_b32 m0, s11
	v_lshl_add_u64 v[2:3], v[106:107], 0, s[34:35]
	s_lshl_b32 s22, s6, 7
	global_load_lds_dwordx4 v[2:3], off sc1
	v_lshl_add_u64 v[6:7], v[2:3], 0, s[30:31]
	s_add_i32 m0, s11, 0x400
	s_ashr_i32 s23, s22, 31
	global_load_lds_dwordx4 v[6:7], off sc1
	v_lshl_add_u64 v[6:7], v[2:3], 0, s[24:25]
	s_add_i32 m0, s11, 0x800
	s_mov_b64 s[16:17], 0xc000
	s_lshl_b64 s[36:37], s[22:23], 11
	global_load_lds_dwordx4 v[6:7], off sc1
	v_lshl_add_u64 v[6:7], v[2:3], 0, s[16:17]
	s_add_i32 m0, s11, 0xc00
	v_lshl_add_u64 v[4:5], v[108:109], 0, s[36:37]
	global_load_lds_dwordx4 v[6:7], off sc1
	s_add_i32 m0, s12, 0x8000
	v_lshl_add_u64 v[6:7], v[4:5], 0, s[30:31]
	global_load_lds_dwordx4 v[4:5], off sc1
	s_add_i32 m0, s12, 0x8400
	s_mov_b64 s[16:17], 0x4080
	global_load_lds_dwordx4 v[6:7], off sc1
	v_lshl_add_u64 v[6:7], v[2:3], 0, s[2:3]
	s_add_i32 m0, s11, 0xc000
	s_mov_b64 s[46:47], 0x8080
	global_load_lds_dwordx4 v[6:7], off sc1
	v_lshl_add_u64 v[6:7], v[2:3], 0, s[16:17]
	s_add_i32 m0, s11, 0xc400
	s_mov_b64 s[48:49], 0x8100
	global_load_lds_dwordx4 v[6:7], off sc1
	v_lshl_add_u64 v[6:7], v[2:3], 0, s[46:47]
	s_add_i32 m0, s11, 0xc800
	s_mov_b64 s[46:47], 0xc080
	global_load_lds_dwordx4 v[6:7], off sc1
	v_lshl_add_u64 v[6:7], v[2:3], 0, s[46:47]
	s_add_i32 m0, s11, 0xcc00
	s_mov_b64 s[46:47], 0x4100
	global_load_lds_dwordx4 v[6:7], off sc1
	v_lshl_add_u64 v[6:7], v[4:5], 0, s[2:3]
	s_add_i32 m0, s12, 0x14000
	v_add_u32_e32 v117, v123, v124
	global_load_lds_dwordx4 v[6:7], off sc1
	v_lshl_add_u64 v[6:7], v[4:5], 0, s[16:17]
	s_add_i32 m0, s12, 0x14400
	s_mov_b64 s[16:17], 0x100
	global_load_lds_dwordx4 v[6:7], off sc1
	v_lshl_add_u64 v[6:7], v[2:3], 0, s[16:17]
	s_add_i32 m0, s11, 0x18000
	v_add_u32_e32 v221, v125, v124
	global_load_lds_dwordx4 v[6:7], off sc1
	v_lshl_add_u64 v[6:7], v[2:3], 0, s[46:47]
	s_add_i32 m0, s11, 0x18400
	v_mov_b32_e32 v34, 0
	global_load_lds_dwordx4 v[6:7], off sc1
	v_lshl_add_u64 v[6:7], v[2:3], 0, s[48:49]
	s_add_i32 m0, s11, 0x18800
	s_mov_b64 s[48:49], 0xc100
	global_load_lds_dwordx4 v[6:7], off sc1
	v_lshl_add_u64 v[2:3], v[2:3], 0, s[48:49]
	s_add_i32 m0, s11, 0x18c00
	v_lshl_add_u64 v[118:119], v[104:105], 0, s[34:35]
	global_load_lds_dwordx4 v[2:3], off sc1
	v_lshl_add_u64 v[2:3], v[4:5], 0, s[16:17]
	s_add_i32 m0, s12, 0x20000
	v_lshl_add_u64 v[120:121], v[114:115], 0, s[36:37]
	global_load_lds_dwordx4 v[2:3], off sc1
	v_lshl_add_u64 v[2:3], v[4:5], 0, s[46:47]
	s_add_i32 m0, s12, 0x20400
	s_mov_b32 s6, -1
	global_load_lds_dwordx4 v[2:3], off sc1
	s_waitcnt vmcnt(12)
	s_waitcnt lgkmcnt(0)
	s_barrier
	ds_read_b128 v[30:33], v117
	ds_read_b128 v[26:29], v221 offset:2048
	ds_read_b128 v[14:17], v221 offset:4096
	ds_read_b128 v[2:5], v221 offset:6144
	ds_read_b128 v[22:25], v210 offset:32768
	ds_read_b128 v[18:21], v212 offset:34816
	ds_read_b128 v[10:13], v212 offset:36864
	ds_read_b128 v[6:9], v212 offset:38912
	s_mov_b32 s13, 0
	s_mov_b32 s14, 1
	s_mov_b32 s19, 0
	v_mov_b32_e32 v35, v34
	v_mov_b32_e32 v36, v34
	v_mov_b32_e32 v37, v34
	v_mov_b32_e32 v42, v34
	v_mov_b32_e32 v43, v34
	v_mov_b32_e32 v44, v34
	v_mov_b32_e32 v45, v34
	v_mov_b32_e32 v46, v34
	v_mov_b32_e32 v47, v34
	v_mov_b32_e32 v48, v34
	v_mov_b32_e32 v49, v34
	v_mov_b32_e32 v50, v34
	v_mov_b32_e32 v51, v34
	v_mov_b32_e32 v52, v34
	v_mov_b32_e32 v53, v34
	v_mov_b32_e32 v54, v34
	v_mov_b32_e32 v55, v34
	v_mov_b32_e32 v56, v34
	v_mov_b32_e32 v57, v34
	v_mov_b32_e32 v58, v34
	v_mov_b32_e32 v59, v34
	v_mov_b32_e32 v60, v34
	v_mov_b32_e32 v61, v34
	v_mov_b32_e32 v62, v34
	v_mov_b32_e32 v63, v34
	v_mov_b32_e32 v64, v34
	v_mov_b32_e32 v65, v34
	v_mov_b32_e32 v66, v34
	v_mov_b32_e32 v67, v34
	v_mov_b32_e32 v68, v34
	v_mov_b32_e32 v69, v34
	v_mov_b32_e32 v70, v34
	v_mov_b32_e32 v71, v34
	v_mov_b32_e32 v72, v34
	v_mov_b32_e32 v73, v34
	v_mov_b32_e32 v74, v34
	v_mov_b32_e32 v75, v34
	v_mov_b32_e32 v76, v34
	v_mov_b32_e32 v77, v34
	v_mov_b32_e32 v78, v34
	v_mov_b32_e32 v79, v34
	v_mov_b32_e32 v80, v34
	v_mov_b32_e32 v81, v34
	v_mov_b32_e32 v82, v34
	v_mov_b32_e32 v83, v34
	v_mov_b32_e32 v84, v34
	v_mov_b32_e32 v85, v34
	v_mov_b32_e32 v94, v34
	v_mov_b32_e32 v95, v34
	v_mov_b32_e32 v96, v34
	v_mov_b32_e32 v97, v34
	v_mov_b32_e32 v86, v34
	v_mov_b32_e32 v87, v34
	v_mov_b32_e32 v88, v34
	v_mov_b32_e32 v89, v34
	v_mov_b32_e32 v90, v34
	v_mov_b32_e32 v91, v34
	v_mov_b32_e32 v92, v34
	v_mov_b32_e32 v93, v34
	v_mov_b32_e32 v38, v34
	v_mov_b32_e32 v39, v34
	v_mov_b32_e32 v40, v34
	v_mov_b32_e32 v41, v34
.LBB0_347:
	s_mul_hi_u32 s20, s19, 0xaaaaaaab
	s_lshr_b32 s20, s20, 1
	s_mul_i32 s20, s20, 0x24000
	s_waitcnt lgkmcnt(0)
	v_mfma_f32_16x16x32_bf16 v[82:85], v[26:29], v[22:25], v[82:85]
	v_add_u32_e32 v191, s13, v122
	s_mul_hi_u32 s23, s14, 0xaaaaaaab
	s_lshr_b32 s23, s23, 1
	v_mfma_f32_16x16x32_bf16 v[78:81], v[26:29], v[18:21], v[78:81]
	s_mul_i32 s23, s23, 0x24000
	v_subrev_u32_e32 v250, s23, v182
	v_subrev_u32_e32 v251, s23, v201
	v_mfma_f32_16x16x32_bf16 v[74:77], v[26:29], v[10:13], v[74:77]
	v_subrev_u32_e32 v252, s23, v202
	v_mfma_f32_16x16x32_bf16 v[70:73], v[26:29], v[6:9], v[70:73]
	v_subrev_u32_e32 v26, s20, v181
	v_mfma_f32_16x16x32_bf16 v[66:69], v[14:17], v[22:25], v[66:69]
	v_mfma_f32_16x16x32_bf16 v[62:65], v[14:17], v[18:21], v[62:65]
	v_mfma_f32_16x16x32_bf16 v[58:61], v[14:17], v[10:13], v[58:61]
	v_mfma_f32_16x16x32_bf16 v[54:57], v[14:17], v[6:9], v[54:57]
	v_subrev_u32_e32 v14, s20, v203
	v_add_u32_e32 v16, v191, v26
	v_add_u32_e32 v14, v191, v14
	v_mfma_f32_16x16x32_bf16 v[38:41], v[30:33], v[22:25], v[38:41]
	v_subrev_u32_e32 v15, s23, v204
	v_mfma_f32_16x16x32_bf16 v[50:53], v[2:5], v[22:25], v[50:53]
	ds_read_b128 v[22:25], v16
	ds_read_b128 v[222:225], v16 offset:2048
	ds_read_b128 v[226:229], v16 offset:4096
	ds_read_b128 v[230:233], v16 offset:6144
	ds_read_b128 v[234:237], v14 offset:32768
	ds_read_b128 v[238:241], v14 offset:34816
	ds_read_b128 v[242:245], v14 offset:36864
	ds_read_b128 v[246:249], v14 offset:38912
	v_mfma_f32_16x16x32_bf16 v[90:93], v[30:33], v[18:21], v[90:93]
	v_mfma_f32_16x16x32_bf16 v[86:89], v[30:33], v[10:13], v[86:89]
	v_mfma_f32_16x16x32_bf16 v[94:97], v[30:33], v[6:9], v[94:97]
	v_mfma_f32_16x16x32_bf16 v[46:49], v[2:5], v[18:21], v[46:49]
	v_mfma_f32_16x16x32_bf16 v[42:45], v[2:5], v[10:13], v[42:45]
	v_mfma_f32_16x16x32_bf16 v[34:37], v[2:5], v[6:9], v[34:37]
	s_add_i32 s20, s6, 4
	s_mul_i32 s23, s20, 0xab
	s_bfe_u32 s23, s23, 0x70009
	s_mul_i32 s23, s23, 3
	s_sub_i32 s20, s20, s23
	s_and_b32 s20, s20, 0xff
	s_mul_i32 s20, s20, 0xc000
	s_waitcnt vmcnt(6)
	v_add_u32_e32 v2, v191, v15
	v_add_u32_e32 v6, v191, v252
	s_waitcnt lgkmcnt(0)
	v_mfma_f32_16x16x32_bf16 v[82:85], v[222:225], v[234:237], v[82:85]
	s_add_i32 s23, s20, s11
	s_waitcnt lgkmcnt(0)
	s_barrier
	v_mfma_f32_16x16x32_bf16 v[78:81], v[222:225], v[238:241], v[78:81]
	ds_read_b128 v[30:33], v2
	ds_read_b128 v[26:29], v2 offset:2048
	ds_read_b128 v[14:17], v2 offset:4096
	ds_read_b128 v[2:5], v2 offset:6144
	v_add_u32_e32 v7, v191, v251
	v_mfma_f32_16x16x32_bf16 v[74:77], v[222:225], v[242:245], v[74:77]
	s_mov_b32 m0, s23
	s_mov_b64 s[34:35], 0x180
	s_add_i32 s20, s20, s12
	v_mfma_f32_16x16x32_bf16 v[70:73], v[222:225], v[246:249], v[70:73]
	v_lshl_add_u64 v[222:223], v[118:119], 0, v[102:103]
	v_lshl_add_u64 v[224:225], v[222:223], 0, s[84:85]
	s_add_i32 s19, s19, 1
	v_mfma_f32_16x16x32_bf16 v[38:41], v[22:25], v[234:237], v[38:41]
	v_mfma_f32_16x16x32_bf16 v[90:93], v[22:25], v[238:241], v[90:93]
	v_mfma_f32_16x16x32_bf16 v[86:89], v[22:25], v[242:245], v[86:89]
	v_mfma_f32_16x16x32_bf16 v[94:97], v[22:25], v[246:249], v[94:97]
	ds_read_b128 v[22:25], v6
	ds_read_b128 v[18:21], v7
	v_add_u32_e32 v6, v191, v250
	ds_read_b128 v[10:13], v6
	ds_read_b128 v[6:9], v6 offset:2048
	global_load_lds_dwordx4 v[224:225], off sc1
	v_lshl_add_u64 v[224:225], v[222:223], 0, s[76:77]
	s_add_i32 m0, s23, 0x400
	v_mfma_f32_16x16x32_bf16 v[66:69], v[226:229], v[234:237], v[66:69]
	global_load_lds_dwordx4 v[224:225], off sc1
	v_lshl_add_u64 v[224:225], v[222:223], 0, s[54:55]
	s_add_i32 m0, s23, 0x800
	v_lshl_add_u64 v[222:223], v[222:223], 0, s[68:69]
	global_load_lds_dwordx4 v[224:225], off sc1
	s_add_i32 m0, s23, 0xc00
	v_mfma_f32_16x16x32_bf16 v[62:65], v[226:229], v[238:241], v[62:65]
	global_load_lds_dwordx4 v[222:223], off sc1
	v_lshl_add_u64 v[222:223], v[120:121], 0, v[102:103]
	v_lshl_add_u64 v[224:225], v[222:223], 0, s[34:35]
	s_add_i32 m0, s20, 0x8000
	s_mov_b64 s[34:35], 0x4180
	global_load_lds_dwordx4 v[224:225], off sc1
	v_lshl_add_u64 v[222:223], v[222:223], 0, s[34:35]
	s_add_i32 m0, s20, 0x8400
	v_mfma_f32_16x16x32_bf16 v[58:61], v[226:229], v[242:245], v[58:61]
	global_load_lds_dwordx4 v[222:223], off sc1
	v_mfma_f32_16x16x32_bf16 v[54:57], v[226:229], v[246:249], v[54:57]
	v_mfma_f32_16x16x32_bf16 v[50:53], v[230:233], v[234:237], v[50:53]
	v_mfma_f32_16x16x32_bf16 v[46:49], v[230:233], v[238:241], v[46:49]
	v_mfma_f32_16x16x32_bf16 v[42:45], v[230:233], v[242:245], v[42:45]
	v_mfma_f32_16x16x32_bf16 v[34:37], v[230:233], v[246:249], v[34:37]
	s_add_i32 s6, s6, 1
	s_add_i32 s13, s13, 0xc000
	s_add_i32 s14, s14, 1
	v_lshl_add_u64 v[118:119], v[118:119], 0, s[2:3]
	s_cmp_eq_u32 s13, 0x9c000
	v_lshl_add_u64 v[120:121], v[120:121], 0, s[2:3]
	s_cbranch_scc0 .LBB0_347
	s_waitcnt lgkmcnt(0)
	v_mfma_f32_16x16x32_bf16 v[38:41], v[30:33], v[22:25], v[38:41]
	v_mfma_f32_16x16x32_bf16 v[90:93], v[30:33], v[18:21], v[90:93]
	v_mfma_f32_16x16x32_bf16 v[86:89], v[30:33], v[10:13], v[86:89]
	v_mfma_f32_16x16x32_bf16 v[30:33], v[30:33], v[6:9], v[94:97]
	v_mfma_f32_16x16x32_bf16 v[82:85], v[26:29], v[22:25], v[82:85]
	v_mfma_f32_16x16x32_bf16 v[78:81], v[26:29], v[18:21], v[78:81]
	v_mfma_f32_16x16x32_bf16 v[74:77], v[26:29], v[10:13], v[74:77]
	v_mfma_f32_16x16x32_bf16 v[26:29], v[26:29], v[6:9], v[70:73]
	v_mfma_f32_16x16x32_bf16 v[66:69], v[14:17], v[22:25], v[66:69]
	v_mfma_f32_16x16x32_bf16 v[62:65], v[14:17], v[18:21], v[62:65]
	v_mfma_f32_16x16x32_bf16 v[58:61], v[14:17], v[10:13], v[58:61]
	v_mfma_f32_16x16x32_bf16 v[14:17], v[14:17], v[6:9], v[54:57]
	v_mfma_f32_16x16x32_bf16 v[22:25], v[2:5], v[22:25], v[50:53]
	v_mfma_f32_16x16x32_bf16 v[18:21], v[2:5], v[18:21], v[46:49]
	s_nop 2
	ds_read_b128 v[46:49], v205
	ds_read_b128 v[50:53], v206 offset:2048
	ds_read_b128 v[54:57], v206 offset:4096
	ds_read_b128 v[70:73], v206 offset:6144
	v_mfma_f32_16x16x32_bf16 v[10:13], v[2:5], v[10:13], v[42:45]
	s_nop 2
	ds_read_b128 v[42:45], v207 offset:32768
	ds_read_b128 v[94:97], v208 offset:34816
	ds_read_b128 v[118:121], v208 offset:36864
	ds_read_b128 v[222:225], v208 offset:38912
	v_mfma_f32_16x16x32_bf16 v[2:5], v[2:5], v[6:9], v[34:37]
	s_waitcnt lgkmcnt(0)
	v_mfma_f32_16x16x32_bf16 v[6:9], v[46:49], v[42:45], v[38:41]
	s_waitcnt vmcnt(6)
	s_waitcnt lgkmcnt(0)
	s_barrier
	v_mfma_f32_16x16x32_bf16 v[34:37], v[46:49], v[94:97], v[90:93]
	v_mfma_f32_16x16x32_bf16 v[38:41], v[46:49], v[118:121], v[86:89]
	s_nop 1
	v_add_u32_e32 v90, 0x20800, v212
	v_mfma_f32_16x16x32_bf16 v[30:33], v[46:49], v[222:225], v[30:33]
	v_mfma_f32_16x16x32_bf16 v[46:49], v[50:53], v[42:45], v[82:85]
	v_mfma_f32_16x16x32_bf16 v[78:81], v[50:53], v[94:97], v[78:81]
	v_mfma_f32_16x16x32_bf16 v[74:77], v[50:53], v[118:121], v[74:77]
	v_mfma_f32_16x16x32_bf16 v[26:29], v[50:53], v[222:225], v[26:29]
	v_mfma_f32_16x16x32_bf16 v[50:53], v[54:57], v[42:45], v[66:69]
	v_mfma_f32_16x16x32_bf16 v[62:65], v[54:57], v[94:97], v[62:65]
	v_mfma_f32_16x16x32_bf16 v[58:61], v[54:57], v[118:121], v[58:61]
	v_mfma_f32_16x16x32_bf16 v[14:17], v[54:57], v[222:225], v[14:17]
	v_add_u32_e32 v54, v180, v124
	ds_read_b128 v[54:57], v54
	ds_read_b128 v[66:69], v209 offset:2048
	v_mfma_f32_16x16x32_bf16 v[18:21], v[70:73], v[94:97], v[18:21]
	v_add_u32_e32 v94, 0x21000, v212
	v_mfma_f32_16x16x32_bf16 v[10:13], v[70:73], v[118:121], v[10:13]
	v_add_u32_e32 v118, 0x21800, v212
	v_mfma_f32_16x16x32_bf16 v[22:25], v[70:73], v[42:45], v[22:25]
	ds_read_b128 v[42:45], v209 offset:4096
	ds_read_b128 v[82:85], v209 offset:6144
	ds_read_b128 v[86:89], v211
	ds_read_b128 v[90:93], v90
	ds_read_b128 v[94:97], v94
	ds_read_b128 v[118:121], v118
	v_mfma_f32_16x16x32_bf16 v[2:5], v[70:73], v[222:225], v[2:5]
	s_waitcnt lgkmcnt(0)
	v_mfma_f32_16x16x32_bf16 v[50:53], v[42:45], v[86:89], v[50:53]
	v_mfma_f32_16x16x32_bf16 v[62:65], v[42:45], v[90:93], v[62:65]
	v_mfma_f32_16x16x32_bf16 v[58:61], v[42:45], v[94:97], v[58:61]
	v_mfma_f32_16x16x32_bf16 v[14:17], v[42:45], v[118:121], v[14:17]
	v_add_u32_e32 v42, v180, v128
	v_mfma_f32_16x16x32_bf16 v[6:9], v[54:57], v[86:89], v[6:9]
	v_mfma_f32_16x16x32_bf16 v[34:37], v[54:57], v[90:93], v[34:37]
	v_mfma_f32_16x16x32_bf16 v[38:41], v[54:57], v[94:97], v[38:41]
	v_mfma_f32_16x16x32_bf16 v[30:33], v[54:57], v[118:121], v[30:33]
	v_mfma_f32_16x16x32_bf16 v[46:49], v[66:69], v[86:89], v[46:49]
	v_mfma_f32_16x16x32_bf16 v[54:57], v[66:69], v[90:93], v[78:81]
	v_mfma_f32_16x16x32_bf16 v[70:73], v[66:69], v[94:97], v[74:77]
	v_mfma_f32_16x16x32_bf16 v[26:29], v[66:69], v[118:121], v[26:29]
	ds_read_b128 v[42:45], v42
	ds_read_b128 v[66:69], v213
	ds_read_b128 v[74:77], v214
	ds_read_b128 v[78:81], v215
	v_mfma_f32_16x16x32_bf16 v[22:25], v[82:85], v[86:89], v[22:25]
	v_mfma_f32_16x16x32_bf16 v[18:21], v[82:85], v[90:93], v[18:21]
	v_mfma_f32_16x16x32_bf16 v[10:13], v[82:85], v[94:97], v[10:13]
	ds_read_b128 v[86:89], v216
	ds_read_b128 v[90:93], v217
	ds_read_b128 v[94:97], v218
	ds_read_b128 v[222:225], v219
	v_mfma_f32_16x16x32_bf16 v[2:5], v[82:85], v[118:121], v[2:5]
	s_waitcnt vmcnt(0)
	s_waitcnt lgkmcnt(0)
	v_mfma_f32_16x16x32_bf16 v[6:9], v[42:45], v[86:89], v[6:9]
	s_waitcnt lgkmcnt(0)
	s_barrier
	v_mfma_f32_16x16x32_bf16 v[34:37], v[42:45], v[90:93], v[34:37]
	v_mfma_f32_16x16x32_bf16 v[38:41], v[42:45], v[94:97], v[38:41]
	v_mfma_f32_16x16x32_bf16 v[30:33], v[42:45], v[222:225], v[30:33]
	v_mfma_f32_16x16x32_bf16 v[42:45], v[66:69], v[86:89], v[46:49]
	v_mfma_f32_16x16x32_bf16 v[46:49], v[66:69], v[90:93], v[54:57]
	v_mfma_f32_16x16x32_bf16 v[54:57], v[66:69], v[94:97], v[70:73]
	v_mfma_f32_16x16x32_bf16 v[26:29], v[66:69], v[222:225], v[26:29]
	v_mfma_f32_16x16x32_bf16 v[50:53], v[74:77], v[86:89], v[50:53]
	v_mfma_f32_16x16x32_bf16 v[62:65], v[74:77], v[90:93], v[62:65]
	v_mfma_f32_16x16x32_bf16 v[58:61], v[74:77], v[94:97], v[58:61]
	v_mfma_f32_16x16x32_bf16 v[14:17], v[74:77], v[222:225], v[14:17]
	ds_read_b128 v[66:69], v212 offset:38912
	ds_read_b128 v[70:73], v212 offset:36864
	ds_read_b128 v[74:77], v212 offset:34816
	ds_read_b128 v[82:85], v210 offset:32768
	v_mfma_f32_16x16x32_bf16 v[22:25], v[78:81], v[86:89], v[22:25]
	v_mfma_f32_16x16x32_bf16 v[18:21], v[78:81], v[90:93], v[18:21]
	v_mfma_f32_16x16x32_bf16 v[10:13], v[78:81], v[94:97], v[10:13]
	ds_read_b128 v[86:89], v221 offset:6144
	ds_read_b128 v[90:93], v221 offset:4096
	ds_read_b128 v[94:97], v221 offset:2048
	ds_read_b128 v[118:121], v117
	v_mfma_f32_16x16x32_bf16 v[2:5], v[78:81], v[222:225], v[2:5]
	s_waitcnt lgkmcnt(0)
	v_mfma_f32_16x16x32_bf16 v[42:45], v[94:97], v[82:85], v[42:45]
	v_add_u32_e32 v78, v123, v128
	v_add_u32_e32 v117, v127, v128
	v_mfma_f32_16x16x32_bf16 v[46:49], v[94:97], v[74:77], v[46:49]
	v_mfma_f32_16x16x32_bf16 v[54:57], v[94:97], v[70:73], v[54:57]
	v_mfma_f32_16x16x32_bf16 v[26:29], v[94:97], v[66:69], v[26:29]
	v_add_u32_e32 v94, v126, v128
	v_mfma_f32_16x16x32_bf16 v[50:53], v[90:93], v[82:85], v[50:53]
	v_mfma_f32_16x16x32_bf16 v[62:65], v[90:93], v[74:77], v[62:65]
	v_mfma_f32_16x16x32_bf16 v[58:61], v[90:93], v[70:73], v[58:61]
	v_mfma_f32_16x16x32_bf16 v[14:17], v[90:93], v[66:69], v[14:17]
	v_add_u32_e32 v90, v125, v128
	v_mfma_f32_16x16x32_bf16 v[6:9], v[118:121], v[82:85], v[6:9]
	v_mfma_f32_16x16x32_bf16 v[34:37], v[118:121], v[74:77], v[34:37]
	v_mfma_f32_16x16x32_bf16 v[38:41], v[118:121], v[70:73], v[38:41]
	v_mfma_f32_16x16x32_bf16 v[30:33], v[118:121], v[66:69], v[30:33]
	v_mfma_f32_16x16x32_bf16 v[22:25], v[86:89], v[82:85], v[22:25]
	ds_read_b128 v[78:81], v78
	ds_read_b128 v[82:85], v90 offset:2048
	v_mfma_f32_16x16x32_bf16 v[18:21], v[86:89], v[74:77], v[18:21]
	ds_read_b128 v[74:77], v90 offset:4096
	ds_read_b128 v[90:93], v90 offset:6144
	v_mfma_f32_16x16x32_bf16 v[10:13], v[86:89], v[70:73], v[10:13]
	ds_read_b128 v[70:73], v94 offset:32768
	ds_read_b128 v[94:97], v117 offset:34816
	ds_read_b128 v[118:121], v117 offset:36864
	ds_read_b128 v[222:225], v117 offset:38912
	v_mfma_f32_16x16x32_bf16 v[2:5], v[86:89], v[66:69], v[2:5]
	s_waitcnt vmcnt(0)
	s_waitcnt lgkmcnt(0)
	s_waitcnt lgkmcnt(0)
	v_mfma_f32_16x16x32_bf16 v[6:9], v[78:81], v[70:73], v[6:9]
	s_barrier
	v_mfma_f32_16x16x32_bf16 v[34:37], v[78:81], v[94:97], v[34:37]
	v_mfma_f32_16x16x32_bf16 v[38:41], v[78:81], v[118:121], v[38:41]
	v_mfma_f32_16x16x32_bf16 v[30:33], v[78:81], v[222:225], v[30:33]
	v_mfma_f32_16x16x32_bf16 v[42:45], v[82:85], v[70:73], v[42:45]
	v_mfma_f32_16x16x32_bf16 v[46:49], v[82:85], v[94:97], v[46:49]
	v_mfma_f32_16x16x32_bf16 v[54:57], v[82:85], v[118:121], v[54:57]
	v_mfma_f32_16x16x32_bf16 v[26:29], v[82:85], v[222:225], v[26:29]
	v_mfma_f32_16x16x32_bf16 v[50:53], v[74:77], v[70:73], v[50:53]
	v_mfma_f32_16x16x32_bf16 v[62:65], v[74:77], v[94:97], v[62:65]
	v_mfma_f32_16x16x32_bf16 v[58:61], v[74:77], v[118:121], v[58:61]
	v_mfma_f32_16x16x32_bf16 v[14:17], v[74:77], v[222:225], v[14:17]
	v_mfma_f32_16x16x32_bf16 v[22:25], v[90:93], v[70:73], v[22:25]
	v_mfma_f32_16x16x32_bf16 v[18:21], v[90:93], v[94:97], v[18:21]
	v_mfma_f32_16x16x32_bf16 v[10:13], v[90:93], v[118:121], v[10:13]
	v_mfma_f32_16x16x32_bf16 v[2:5], v[90:93], v[222:225], v[2:5]
	s_waitcnt lgkmcnt(0)
	s_barrier
	s_mov_b32 s67, 0
	v_readlane_b32 s64, v255, 40
	s_cmp_eq_u32 s64, 0
	s_cbranch_scc1 .Lip_noasync
	v_readlane_b32 s65, v255, 57
	s_add_i32 s65, s75, s65
	s_cmpk_gt_i32 s65, 0x287
	s_cbranch_scc1 .Lip_noasync
	s_mul_hi_i32 s46, s65, 0x2aaaaaab
	s_lshr_b32 s47, s46, 31
	s_ashr_i32 s46, s46, 2
	s_add_i32 s46, s46, s47
	s_mul_i32 s46, s46, 24
	s_sub_i32 s65, s65, s46
	s_lshl_b32 s65, s65, 7
	v_and_b32_e32 v246, 7, v137
	v_lshlrev_b32_e32 v246, 4, v246
	v_add_u32_e32 v246, s65, v246
	s_add_u32 s46, s94, 0xcbcc000
	s_addc_u32 s47, s95, 0
	global_load_dwordx4 v[242:245], v246, s[46:47] sc1
	s_mov_b32 s67, 1
.Lip_noasync:
	v_mov_b32_e32 v230, s75
	v_mov_b32_e32 v231, 0xaaaaaaab
	v_mul_hi_u32 v231, v230, v231
	v_lshrrev_b32_e32 v231, 4, v231
	v_cmp_gt_u32_e32 vcc, 26, v231
	s_nop 4
	s_cmp_lg_u64 vcc, 0
	s_cbranch_scc0 .Lipe_fallback
	s_mul_hi_i32 s6, s75, 0x2aaaaaab
	s_lshr_b32 s13, s6, 31
	s_ashr_i32 s6, s6, 2
	s_add_i32 s6, s6, s13
	s_mul_i32 s13, s6, 24
	s_sub_i32 s13, s75, s13
	v_readfirstlane_b32 s14, v137
	s_lshr_b32 s14, s14, 6
	s_and_b32 s19, s14, 1
	s_lshr_b32 s20, s14, 1
	s_lshl_b32 s13, s13, 8
	s_lshl_b32 s20, s20, 6
	s_add_i32 s13, s13, s20
	s_lshl_b32 s6, s6, 7
	s_lshl_b32 s19, s19, 6
	s_add_i32 s6, s6, s19
	s_mul_i32 s14, s14, 0x4100
	s_lshr_b32 s20, s6, 8
	s_cmpk_lt_i32 s13, 0x1000
	s_cselect_b32 s19, 1, 0
	s_and_b32 s46, s13, 0xff
	s_add_i32 s47, s13, 0xfffff000
	s_and_b32 s47, s47, 0x3ff
	s_cmp_lg_u32 s19, 0
	s_cselect_b32 s46, s46, s47
	s_sub_i32 s47, s13, s46
	v_and_b32_e32 v221, 63, v137
	v_and_b32_e32 v222, 15, v221
	v_lshrrev_b32_e32 v223, 4, v221
	v_and_b32_e32 v224, 3, v222
	v_lshrrev_b32_e32 v225, 2, v222
	v_lshl_or_b32 v226, v223, 2, v224
	v_lshl_add_u32 v232, v221, 4, s14
	v_lshrrev_b32_e32 v236, 3, v221
	v_and_b32_e32 v237, 7, v221
	v_xor_b32_e32 v237, v237, v236
	s_mov_b32 s16, 0xd30
	s_lshr_b32 s16, s16, s20
	s_and_b32 s16, s16, 1
	s_cbranch_scc0 .Lipe_noT
	s_mov_b32 s22, 0xae78000
	s_mov_b32 s23, 9
	s_sub_i32 s26, s6, 1024
	s_add_i32 s27, s6, 0xfffff800
	s_cmp_eq_u32 s20, 8
	s_cselect_b32 s22, 0xb478000, s22
	s_cselect_b32 s23, 8, s23
	s_cselect_b32 s26, s27, s26
	s_add_i32 s27, s6, 0xfffff600
	s_cmp_eq_u32 s20, 10
	s_cselect_b32 s22, 0xba78000, s22
	s_cselect_b32 s23, 8, s23
	s_cselect_b32 s26, s27, s26
	s_add_i32 s27, s6, 0xfffff500
	s_cmp_eq_u32 s20, 11
	s_cselect_b32 s22, 0xb778000, s22
	s_cselect_b32 s23, 8, s23
	s_cselect_b32 s26, s27, s26
	s_lshl_b32 s27, s47, 1
	s_lshl_b32 s27, s27, s23
	s_add_i32 s22, s22, s27
	s_lshr_b32 s27, s46, 5
	s_lshl_b32 s27, s27, 6
	s_lshl_b32 s27, s27, s23
	s_add_i32 s22, s22, s27
	s_lshl_b32 s27, s26, 6
	s_add_i32 s22, s22, s27
	v_lshrrev_b32_e32 v233, 2, v237
	v_lshlrev_b32_e32 v233, 6, v233
	v_lshlrev_b32_e32 v233, s23, v233
	v_lshl_add_u32 v233, v236, 6, v233
	v_and_b32_e32 v234, 3, v237
	v_lshl_add_u32 v233, v234, 4, v233
	v_add_u32_e32 v233, s22, v233
	v_and_b32_e32 v227, 7, v222
	v_lshlrev_b32_e32 v227, 1, v227
	v_or_b32_e32 v228, 0, v223
	v_xor_b32_e32 v228, v228, v227
	v_lshlrev_b32_e32 v228, 3, v228
	v_lshl_add_u32 v228, v222, 7, v228
	v_add_u32_e32 v228, s14, v228
	v_or_b32_e32 v229, 4, v223
	v_xor_b32_e32 v229, v229, v227
	v_lshlrev_b32_e32 v229, 3, v229
	v_lshl_add_u32 v229, v222, 7, v229
	v_add_u32_e32 v229, s14, v229
	v_or_b32_e32 v230, 8, v223
	v_xor_b32_e32 v230, v230, v227
	v_lshlrev_b32_e32 v230, 3, v230
	v_lshl_add_u32 v230, v222, 7, v230
	v_add_u32_e32 v230, s14, v230
	v_or_b32_e32 v231, 12, v223
	v_xor_b32_e32 v231, v231, v227
	v_lshlrev_b32_e32 v231, 3, v231
	v_lshl_add_u32 v231, v222, 7, v231
	v_add_u32_e32 v231, s14, v231
	v_cvt_pk_bf16_f32 v66, v6, v7
	v_cvt_pk_bf16_f32 v67, v8, v9
	ds_write_b64 v228, v[66:67] offset:0
	v_cvt_pk_bf16_f32 v70, v34, v35
	v_cvt_pk_bf16_f32 v71, v36, v37
	ds_write_b64 v228, v[70:71] offset:2048
	v_cvt_pk_bf16_f32 v74, v38, v39
	v_cvt_pk_bf16_f32 v75, v40, v41
	ds_write_b64 v228, v[74:75] offset:4096
	v_cvt_pk_bf16_f32 v78, v30, v31
	v_cvt_pk_bf16_f32 v79, v32, v33
	ds_write_b64 v228, v[78:79] offset:6144
	v_cvt_pk_bf16_f32 v82, v42, v43
	v_cvt_pk_bf16_f32 v83, v44, v45
	ds_write_b64 v229, v[82:83] offset:0
	v_cvt_pk_bf16_f32 v86, v46, v47
	v_cvt_pk_bf16_f32 v87, v48, v49
	ds_write_b64 v229, v[86:87] offset:2048
	v_cvt_pk_bf16_f32 v90, v54, v55
	v_cvt_pk_bf16_f32 v91, v56, v57
	ds_write_b64 v229, v[90:91] offset:4096
	v_cvt_pk_bf16_f32 v94, v26, v27
	v_cvt_pk_bf16_f32 v95, v28, v29
	ds_write_b64 v229, v[94:95] offset:6144
	v_cvt_pk_bf16_f32 v66, v50, v51
	v_cvt_pk_bf16_f32 v67, v52, v53
	ds_write_b64 v230, v[66:67] offset:0
	v_cvt_pk_bf16_f32 v70, v62, v63
	v_cvt_pk_bf16_f32 v71, v64, v65
	ds_write_b64 v230, v[70:71] offset:2048
	v_cvt_pk_bf16_f32 v74, v58, v59
	v_cvt_pk_bf16_f32 v75, v60, v61
	ds_write_b64 v230, v[74:75] offset:4096
	v_cvt_pk_bf16_f32 v78, v14, v15
	v_cvt_pk_bf16_f32 v79, v16, v17
	ds_write_b64 v230, v[78:79] offset:6144
	v_cvt_pk_bf16_f32 v82, v22, v23
	v_cvt_pk_bf16_f32 v83, v24, v25
	ds_write_b64 v231, v[82:83] offset:0
	v_cvt_pk_bf16_f32 v86, v18, v19
	v_cvt_pk_bf16_f32 v87, v20, v21
	ds_write_b64 v231, v[86:87] offset:2048
	v_cvt_pk_bf16_f32 v90, v10, v11
	v_cvt_pk_bf16_f32 v91, v12, v13
	ds_write_b64 v231, v[90:91] offset:4096
	v_cvt_pk_bf16_f32 v94, v2, v3
	v_cvt_pk_bf16_f32 v95, v4, v5
	ds_write_b64 v231, v[94:95] offset:6144
	s_waitcnt lgkmcnt(0)
	ds_read_b128 v[66:69], v232 offset:0
	ds_read_b128 v[70:73], v232 offset:1024
	ds_read_b128 v[74:77], v232 offset:2048
	ds_read_b128 v[78:81], v232 offset:3072
	ds_read_b128 v[82:85], v232 offset:4096
	ds_read_b128 v[86:89], v232 offset:5120
	ds_read_b128 v[90:93], v232 offset:6144
	ds_read_b128 v[94:97], v232 offset:7168
	s_waitcnt lgkmcnt(7)
	global_store_dwordx4 v233, v[66:69], s[94:95]
	s_waitcnt lgkmcnt(6)
	v_add_u32_e32 v235, 0x200, v233
	global_store_dwordx4 v235, v[70:73], s[94:95]
	s_waitcnt lgkmcnt(5)
	v_add_u32_e32 v235, 0x400, v233
	global_store_dwordx4 v235, v[74:77], s[94:95]
	s_waitcnt lgkmcnt(4)
	v_add_u32_e32 v235, 0x600, v233
	global_store_dwordx4 v235, v[78:81], s[94:95]
	s_waitcnt lgkmcnt(3)
	v_add_u32_e32 v235, 0x800, v233
	global_store_dwordx4 v235, v[82:85], s[94:95]
	s_waitcnt lgkmcnt(2)
	v_add_u32_e32 v235, 0xa00, v233
	global_store_dwordx4 v235, v[86:89], s[94:95]
	s_waitcnt lgkmcnt(1)
	v_add_u32_e32 v235, 0xc00, v233
	global_store_dwordx4 v235, v[90:93], s[94:95]
	s_waitcnt lgkmcnt(0)
	v_add_u32_e32 v235, 0xe00, v233
	global_store_dwordx4 v235, v[94:97], s[94:95]
	s_nop 1

.Lln2_end:
	s_waitcnt vmcnt(0)
	s_barrier
	v_readfirstlane_b32 s13, v137
	s_cmp_lt_u32 s13, 64
	s_cbranch_scc0 .Lln2_nodone
	s_mul_hi_i32 s19, s70, 0x2aaaaaab
	s_lshr_b32 s13, s19, 31
	s_ashr_i32 s19, s19, 2
	s_add_i32 s19, s19, s13
	s_mul_i32 s13, s19, 24
	s_sub_i32 s13, s70, s13
	s_lshl_b32 s13, s13, 3
	s_add_i32 s13, s13, s19
	s_lshl_b32 s13, s13, 4
	v_readlane_b32 s14, v255, 40
	s_add_i32 s14, s14, 0x5d0e3000
	v_mov_b32_e32 v247, s13
	v_mov_b32_e32 v248, s14
	v_mov_b32_e32 v249, s14
	v_mov_b32_e32 v250, s14
	v_mov_b32_e32 v251, s14
	s_add_u32 s36, s94, 0xcbcc000
	s_addc_u32 s37, s95, 0
	s_mov_b64 exec, 1
	global_store_dwordx4 v247, v[248:251], s[36:37] sc1
	s_mov_b64 exec, -1
